# nextitempf: P5 copy waves with two items touch the second (w_o) item's source tile into L2 before the first item's loads
# baseline (speedup 1.0000x reference)
.LBB0_1045:
	s_add_i32 s98, s26, s2
	s_sub_i32 s98, s98, 0x1980
	s_cmpk_lt_u32 s98, 0x100
	s_cbranch_scc0 .Lnpf_skip
	s_add_i32 s98, s27, s28
	s_and_b32 s98, s98, 0x3c0
	s_lshl_b32 s98, s98, 2
	s_mov_b32 s99, 0
	v_lshl_add_u64 v[242:243], v[86:87], 0, s[98:99]
	s_add_i32 s98, s31, s34
	s_and_b32 s98, s98, 0x7fffffc0
	s_addk_i32 s98, 0x9a00
	v_or_b32_e32 v240, s98, v66
	v_mov_b32_e32 v241, 0
	v_lshlrev_b64 v[244:245], 12, v[240:241]
	v_lshl_add_u64 v[246:247], v[242:243], 0, v[244:245]
	s_movk_i32 s98, 0x4000
	global_load_dword v250, v[246:247], off
	v_lshl_add_u64 v[246:247], v[246:247], 0, s[98:99]
	global_load_dword v250, v[246:247], off
	v_lshl_add_u64 v[246:247], v[246:247], 0, s[98:99]
	global_load_dword v250, v[246:247], off
	v_lshl_add_u64 v[246:247], v[246:247], 0, s[98:99]
	global_load_dword v250, v[246:247], off
	v_lshl_add_u64 v[246:247], v[246:247], 0, s[98:99]
	global_load_dword v250, v[246:247], off
	v_lshl_add_u64 v[246:247], v[246:247], 0, s[98:99]
	global_load_dword v250, v[246:247], off
	v_lshl_add_u64 v[246:247], v[246:247], 0, s[98:99]
	global_load_dword v250, v[246:247], off
	v_lshl_add_u64 v[246:247], v[246:247], 0, s[98:99]
	global_load_dword v250, v[246:247], off
	v_lshl_add_u64 v[246:247], v[246:247], 0, s[98:99]
	global_load_dword v250, v[246:247], off
	v_lshl_add_u64 v[246:247], v[246:247], 0, s[98:99]
	global_load_dword v250, v[246:247], off
	v_lshl_add_u64 v[246:247], v[246:247], 0, s[98:99]
	global_load_dword v250, v[246:247], off
	v_lshl_add_u64 v[246:247], v[246:247], 0, s[98:99]
	global_load_dword v250, v[246:247], off
	v_lshl_add_u64 v[246:247], v[246:247], 0, s[98:99]
	global_load_dword v250, v[246:247], off
	v_lshl_add_u64 v[246:247], v[246:247], 0, s[98:99]
	global_load_dword v250, v[246:247], off
	v_lshl_add_u64 v[246:247], v[246:247], 0, s[98:99]
	global_load_dword v250, v[246:247], off
	v_lshl_add_u64 v[246:247], v[246:247], 0, s[98:99]
	global_load_dword v250, v[246:247], off
